# convert_tile: issue the four per-row gain loads together instead of four serialized vmcnt(0) round trips
# baseline (speedup 1.0000x reference)
; DI void convert_tile(const float* __restrict__ W, int K, int N, const float* __restrict__ g, bf16_t* __restrict__ Wt, int mode, int kt, int nt, bool f16) {
;     ...
;   float* tile = (float*)smem;
;   {
;     const int nl = (t & 31) * 4;
;     const int n = nt * 128 + nl;
;     const int nc = min(n, N - 4);
;     float4 v[4];
; #pragma unroll
;     for (int i = 0; i < 4; ++i) v[i] = *(const float4*)(W + (size_t)(kt * 64 + (t >> 5) + 16 * i) * N + nc);
; #pragma unroll
;     for (int i = 0; i < 4; ++i) {
;       const int kl = (t >> 5) + 16 * i;
;       const float gs = g ? g[kt * 64 + kl] : 1.f;
;       tile[kl * 129 + nl + 0] = v[i].x * gs;
;       tile[kl * 129 + nl + 1] = v[i].y * gs;
;       tile[kl * 129 + nl + 2] = v[i].z * gs;
;       tile[kl * 129 + nl + 3] = v[i].w * gs;
;     }
.LBB0_50:
	s_mul_hi_i32 s16, s25, 0x2aaaaaab
	s_lshr_b32 s17, s16, 31
	s_ashr_i32 s16, s16, 1
	v_mov_b32_e32 v22, v224
	s_add_i32 s16, s16, s17
	s_mul_i32 s17, s16, 0x600
	v_lshlrev_b32_e32 v0, 2, v22
	v_and_b32_e32 v23, 0x7c, v0
	v_subrev_u32_e32 v0, s17, v23
	v_add_u32_e32 v0, s20, v0
	v_min_i32_e32 v0, 0x5fc, v0
	s_lshl_b32 s16, s16, 6
	v_ashrrev_i32_e32 v24, 5, v22
	v_ashrrev_i32_e32 v1, 31, v0
	v_add_u32_e32 v18, s16, v24
	v_lshl_add_u64 v[0:1], v[0:1], 2, s[12:13]
	v_mad_i64_i32 v[2:3], s[18:19], v18, s23, v[0:1]
	v_add_u32_e32 v4, 16, v18
	v_mad_i64_i32 v[4:5], s[18:19], v4, s23, v[0:1]
	global_load_dwordx4 v[12:15], v[2:3], off
	global_load_dwordx4 v[8:11], v[4:5], off
	v_add_u32_e32 v2, 32, v18
	v_mad_i64_i32 v[26:27], s[18:19], v2, s23, v[0:1]
	v_add_u32_e32 v2, 48, v18
	v_mad_i64_i32 v[28:29], s[18:19], v2, s23, v[0:1]
	global_load_dwordx4 v[4:7], v[26:27], off
	global_load_dwordx4 v[0:3], v[28:29], off
	v_ashrrev_i32_e32 v19, 31, v18
	v_mov_b32_e32 v16, 1.0
	s_and_b64 vcc, exec, s[14:15]
	v_lshl_add_u64 v[18:19], v[18:19], 2, s[8:9]
	v_mov_b32_e32 v20, 1.0
	s_cbranch_vccz .LBB0_52
	global_load_dword v20, v[18:19], off
	global_load_dword v100, v[18:19], off offset:64
	global_load_dword v101, v[18:19], off offset:128
	global_load_dword v102, v[18:19], off offset:192
.LBB0_52:
	v_lshlrev_b32_e32 v23, 2, v23
	s_waitcnt vmcnt(0)
	v_pk_mul_f32 v[26:27], v[12:13], v[20:21] op_sel_hi:[1,0]
	v_mul_lo_u32 v12, v24, s24
	v_add_u32_e32 v12, v23, v12
	v_pk_mul_f32 v[14:15], v[14:15], v[20:21] op_sel_hi:[1,0]
	s_and_b64 vcc, exec, s[4:5]
	ds_write2_b32 v12, v26, v27 offset1:1
	ds_write2_b32 v12, v14, v15 offset0:2 offset1:3
	s_cbranch_vccnz .LBB0_54
	v_mov_b32_e32 v16, v100
.LBB0_54:
	s_waitcnt vmcnt(0)
	v_pk_mul_f32 v[8:9], v[8:9], v[16:17] op_sel_hi:[1,0]
	v_add_u32_e32 v13, 0x2040, v12
	ds_write2_b32 v13, v8, v9 offset1:1
	v_pk_mul_f32 v[8:9], v[10:11], v[16:17] op_sel_hi:[1,0]
	v_add_u32_e32 v10, 0x2048, v12
	ds_write2_b32 v10, v8, v9 offset1:1
	v_mov_b32_e32 v8, 1.0
	s_and_b64 vcc, exec, s[4:5]
	v_mov_b32_e32 v10, 1.0
	s_cbranch_vccnz .LBB0_56
	v_mov_b32_e32 v10, v101
.LBB0_56:
	s_waitcnt vmcnt(0)
	v_pk_mul_f32 v[4:5], v[4:5], v[10:11] op_sel_hi:[1,0]
	v_add_u32_e32 v9, 0x4080, v12
	ds_write2_b32 v9, v4, v5 offset1:1
	v_pk_mul_f32 v[4:5], v[6:7], v[10:11] op_sel_hi:[1,0]
	v_add_u32_e32 v6, 0x4088, v12
	s_and_b64 vcc, exec, s[4:5]
	ds_write2_b32 v6, v4, v5 offset1:1
	s_cbranch_vccnz .LBB0_58
	v_mov_b32_e32 v8, v102

; DI void convert_tile(const float* __restrict__ W, int K, int N, const float* __restrict__ g, bf16_t* __restrict__ Wt, int mode, int kt, int nt, bool f16) {
;     ...
;   float* tile = (float*)smem;
;   {
;     const int nl = (t & 31) * 4;
;     const int n = nt * 128 + nl;
;     const int nc = min(n, N - 4);
;     float4 v[4];
; #pragma unroll
;     for (int i = 0; i < 4; ++i) v[i] = *(const float4*)(W + (size_t)(kt * 64 + (t >> 5) + 16 * i) * N + nc);
; #pragma unroll
;     for (int i = 0; i < 4; ++i) {
;       const int kl = (t >> 5) + 16 * i;
;       const float gs = g ? g[kt * 64 + kl] : 1.f;
;       tile[kl * 129 + nl + 0] = v[i].x * gs;
;       tile[kl * 129 + nl + 1] = v[i].y * gs;
;       tile[kl * 129 + nl + 2] = v[i].z * gs;
;       tile[kl * 129 + nl + 3] = v[i].w * gs;
;     }
.LBB0_68:
	s_ashr_i32 s16, s20, 31
	s_lshr_b32 s16, s16, 30
	s_add_i32 s16, s20, s16
	v_mov_b32_e32 v22, v224
	s_ashr_i32 s16, s16, 2
	s_lshl_b32 s17, s16, 9
	v_lshlrev_b32_e32 v0, 2, v22
	v_and_b32_e32 v23, 0x7c, v0
	v_subrev_u32_e32 v0, s17, v23
	v_add_u32_e32 v0, s21, v0
	s_lshl_b32 s16, s16, 6
	v_ashrrev_i32_e32 v24, 5, v22
	v_min_i32_e32 v0, 0x1fc, v0
	v_add_u32_e32 v18, s16, v24
	v_ashrrev_i32_e32 v1, 31, v0
	v_ashrrev_i32_e32 v19, 31, v18
	v_lshl_add_u64 v[0:1], v[0:1], 2, s[8:9]
	v_lshlrev_b64 v[2:3], 11, v[18:19]
	v_lshl_add_u64 v[0:1], v[0:1], 0, v[2:3]
	v_add_co_u32_e32 v2, vcc, 0x8000, v0
	v_mov_b32_e32 v16, 1.0
	s_nop 0
	v_addc_co_u32_e32 v3, vcc, 0, v1, vcc
	v_add_co_u32_e32 v26, vcc, 0x10000, v0
	global_load_dwordx4 v[12:15], v[0:1], off
	global_load_dwordx4 v[8:11], v[2:3], off
	v_addc_co_u32_e32 v27, vcc, 0, v1, vcc
	v_add_co_u32_e32 v28, vcc, 0x18000, v0
	v_lshl_add_u64 v[18:19], v[18:19], 2, s[6:7]
	s_nop 0
	v_addc_co_u32_e32 v29, vcc, 0, v1, vcc
	global_load_dwordx4 v[4:7], v[26:27], off
	global_load_dwordx4 v[0:3], v[28:29], off
	s_and_b64 vcc, exec, s[14:15]
	v_mov_b32_e32 v20, 1.0
	s_cbranch_vccz .LBB0_70
	global_load_dword v20, v[18:19], off
	global_load_dword v100, v[18:19], off offset:64
	global_load_dword v101, v[18:19], off offset:128
	global_load_dword v102, v[18:19], off offset:192
.LBB0_70:
	v_lshlrev_b32_e32 v23, 2, v23
	s_waitcnt vmcnt(0)
	v_pk_mul_f32 v[26:27], v[12:13], v[20:21] op_sel_hi:[1,0]
	v_mul_lo_u32 v12, v24, s23
	v_add_u32_e32 v12, v23, v12
	v_pk_mul_f32 v[14:15], v[14:15], v[20:21] op_sel_hi:[1,0]
	s_and_b64 vcc, exec, s[4:5]
	ds_write2_b32 v12, v26, v27 offset1:1
	ds_write2_b32 v12, v14, v15 offset0:2 offset1:3
	s_cbranch_vccnz .LBB0_72
	v_mov_b32_e32 v16, v100

; DI void convert_tile(const float* __restrict__ W, int K, int N, const float* __restrict__ g, bf16_t* __restrict__ Wt, int mode, int kt, int nt, bool f16) {
;     ...
;   float* tile = (float*)smem;
;   {
;     const int nl = (t & 31) * 4;
;     const int n = nt * 128 + nl;
;     const int nc = min(n, N - 4);
;     float4 v[4];
; #pragma unroll
;     for (int i = 0; i < 4; ++i) v[i] = *(const float4*)(W + (size_t)(kt * 64 + (t >> 5) + 16 * i) * N + nc);
; #pragma unroll
;     for (int i = 0; i < 4; ++i) {
;       const int kl = (t >> 5) + 16 * i;
;       const float gs = g ? g[kt * 64 + kl] : 1.f;
;       tile[kl * 129 + nl + 0] = v[i].x * gs;
;       tile[kl * 129 + nl + 1] = v[i].y * gs;
;       tile[kl * 129 + nl + 2] = v[i].z * gs;
;       tile[kl * 129 + nl + 3] = v[i].w * gs;
;     }
.LBB0_81:
	s_ashr_i32 s16, s20, 31
	s_lshr_b32 s16, s16, 29
	s_add_i32 s16, s20, s16
	v_mov_b32_e32 v22, v224
	s_ashr_i32 s16, s16, 3
	s_lshl_b32 s17, s16, 10
	v_lshlrev_b32_e32 v0, 2, v22
	v_and_b32_e32 v23, 0x7c, v0
	v_subrev_u32_e32 v0, s17, v23
	v_add_u32_e32 v0, s21, v0
	s_lshl_b32 s16, s16, 6
	v_ashrrev_i32_e32 v24, 5, v22
	v_min_i32_e32 v0, 0x3fc, v0
	v_add_u32_e32 v18, s16, v24
	v_ashrrev_i32_e32 v1, 31, v0
	v_ashrrev_i32_e32 v19, 31, v18
	v_lshl_add_u64 v[0:1], v[0:1], 2, s[8:9]
	v_lshlrev_b64 v[2:3], 12, v[18:19]
	v_lshl_add_u64 v[0:1], v[0:1], 0, v[2:3]
	v_add_co_u32_e32 v2, vcc, 0x10000, v0
	v_mov_b32_e32 v16, 1.0
	s_nop 0
	v_addc_co_u32_e32 v3, vcc, 0, v1, vcc
	v_add_co_u32_e32 v26, vcc, 0x20000, v0
	global_load_dwordx4 v[12:15], v[0:1], off
	global_load_dwordx4 v[8:11], v[2:3], off
	v_addc_co_u32_e32 v27, vcc, 0, v1, vcc
	v_add_co_u32_e32 v28, vcc, 0x30000, v0
	v_lshl_add_u64 v[18:19], v[18:19], 2, s[6:7]
	s_nop 0
	v_addc_co_u32_e32 v29, vcc, 0, v1, vcc
	global_load_dwordx4 v[4:7], v[26:27], off
	global_load_dwordx4 v[0:3], v[28:29], off
	s_and_b64 vcc, exec, s[14:15]
	v_mov_b32_e32 v20, 1.0
	s_cbranch_vccz .LBB0_83
	global_load_dword v20, v[18:19], off
	global_load_dword v100, v[18:19], off offset:64
	global_load_dword v101, v[18:19], off offset:128
	global_load_dword v102, v[18:19], off offset:192

; DI void convert_tile(const float* __restrict__ W, int K, int N, const float* __restrict__ g, bf16_t* __restrict__ Wt, int mode, int kt, int nt, bool f16) {
;     ...
;   float* tile = (float*)smem;
;   {
;     const int nl = (t & 31) * 4;
;     const int n = nt * 128 + nl;
;     const int nc = min(n, N - 4);
;     float4 v[4];
; #pragma unroll
;     for (int i = 0; i < 4; ++i) v[i] = *(const float4*)(W + (size_t)(kt * 64 + (t >> 5) + 16 * i) * N + nc);
; #pragma unroll
;     for (int i = 0; i < 4; ++i) {
;       const int kl = (t >> 5) + 16 * i;
;       const float gs = g ? g[kt * 64 + kl] : 1.f;
;       tile[kl * 129 + nl + 0] = v[i].x * gs;
;       tile[kl * 129 + nl + 1] = v[i].y * gs;
;       tile[kl * 129 + nl + 2] = v[i].z * gs;
;       tile[kl * 129 + nl + 3] = v[i].w * gs;
;     }
.LBB0_100:
	s_mul_hi_i32 s6, s22, 0x2e8ba2e9
	s_lshr_b32 s7, s6, 31
	s_ashr_i32 s6, s6, 3
	v_mov_b32_e32 v23, v224
	s_add_i32 s7, s6, s7
	s_mul_i32 s6, s7, 0x1600
	v_lshlrev_b32_e32 v0, 2, v23
	v_and_b32_e32 v24, 0x7c, v0
	v_subrev_u32_e32 v0, s6, v24
	v_add_u32_e32 v0, s23, v0
	v_min_i32_e32 v0, 0x15fc, v0
	s_lshl_b32 s18, s7, 6
	v_ashrrev_i32_e32 v25, 5, v23
	v_ashrrev_i32_e32 v1, 31, v0
	v_add_u32_e32 v18, s18, v25
	v_lshl_add_u64 v[0:1], v[0:1], 2, s[12:13]
	v_mad_i64_i32 v[2:3], s[20:21], v18, s26, v[0:1]
	v_add_u32_e32 v4, 16, v18
	v_mad_i64_i32 v[4:5], s[20:21], v4, s26, v[0:1]
	global_load_dwordx4 v[12:15], v[2:3], off
	global_load_dwordx4 v[8:11], v[4:5], off
	v_add_u32_e32 v2, 32, v18
	v_mad_i64_i32 v[26:27], s[20:21], v2, s26, v[0:1]
	v_add_u32_e32 v2, 48, v18
	v_mad_i64_i32 v[28:29], s[20:21], v2, s26, v[0:1]
	global_load_dwordx4 v[4:7], v[26:27], off
	global_load_dwordx4 v[0:3], v[28:29], off
	v_ashrrev_i32_e32 v19, 31, v18
	v_mov_b32_e32 v16, 1.0
	s_and_b64 vcc, exec, s[16:17]
	v_lshl_add_u64 v[18:19], v[18:19], 2, s[8:9]
	v_mov_b32_e32 v20, 1.0
	s_cbranch_vccz .LBB0_102
	global_load_dword v20, v[18:19], off
	global_load_dword v100, v[18:19], off offset:64
	global_load_dword v101, v[18:19], off offset:128
	global_load_dword v102, v[18:19], off offset:192
.LBB0_102:
	v_lshlrev_b32_e32 v24, 2, v24
	s_waitcnt vmcnt(0)
	v_pk_mul_f32 v[26:27], v[12:13], v[20:21] op_sel_hi:[1,0]
	v_mul_lo_u32 v12, v25, s27
	v_add_u32_e32 v12, v24, v12
	v_pk_mul_f32 v[14:15], v[14:15], v[20:21] op_sel_hi:[1,0]
	s_and_b64 vcc, exec, s[4:5]
	ds_write2_b32 v12, v26, v27 offset1:1
	ds_write2_b32 v12, v14, v15 offset0:2 offset1:3
	s_cbranch_vccnz .LBB0_104
	v_mov_b32_e32 v16, v100

; DI void convert_tile(const float* __restrict__ W, int K, int N, const float* __restrict__ g, bf16_t* __restrict__ Wt, int mode, int kt, int nt, bool f16) {
;     ...
;   float* tile = (float*)smem;
;   {
;     const int nl = (t & 31) * 4;
;     const int n = nt * 128 + nl;
;     const int nc = min(n, N - 4);
;     float4 v[4];
; #pragma unroll
;     for (int i = 0; i < 4; ++i) v[i] = *(const float4*)(W + (size_t)(kt * 64 + (t >> 5) + 16 * i) * N + nc);
; #pragma unroll
;     for (int i = 0; i < 4; ++i) {
;       const int kl = (t >> 5) + 16 * i;
;       const float gs = g ? g[kt * 64 + kl] : 1.f;
;       tile[kl * 129 + nl + 0] = v[i].x * gs;
;       tile[kl * 129 + nl + 1] = v[i].y * gs;
;       tile[kl * 129 + nl + 2] = v[i].z * gs;
;       tile[kl * 129 + nl + 3] = v[i].w * gs;
;     }
.LBB0_269:
	s_ashr_i32 s4, s29, 31
	s_lshr_b32 s4, s4, 28
	s_add_i32 s4, s29, s4
	v_mov_b32_e32 v3, v224
	s_ashr_i32 s4, s4, 4
	s_lshl_b32 s33, s4, 11
	v_lshlrev_b32_e32 v0, 2, v3
	v_and_b32_e32 v21, 0x7c, v0
	v_subrev_u32_e32 v0, s33, v21
	v_add_u32_e32 v0, s1, v0
	v_min_i32_e32 v0, 0x79c, v0
	s_lshl_b32 s36, s4, 6
	v_ashrrev_i32_e32 v23, 5, v3
	v_ashrrev_i32_e32 v1, 31, v0
	v_add_u32_e32 v24, s36, v23
	v_lshl_add_u64 v[0:1], v[0:1], 2, s[20:21]
	s_movk_i32 s37, 0x1e80
	v_mad_i64_i32 v[4:5], s[4:5], v24, s37, v[0:1]
	v_add_u32_e32 v6, 16, v24
	v_mad_i64_i32 v[6:7], s[4:5], v6, s37, v[0:1]
	global_load_dwordx4 v[16:19], v[4:5], off
	global_load_dwordx4 v[12:15], v[6:7], off
	v_add_u32_e32 v4, 32, v24
	v_mad_i64_i32 v[4:5], s[4:5], v4, s37, v[0:1]
	v_add_u32_e32 v6, 48, v24
	v_mad_i64_i32 v[0:1], s[4:5], v6, s37, v[0:1]
	global_load_dwordx4 v[8:11], v[4:5], off
	s_nop 0
	global_load_dwordx4 v[4:7], v[0:1], off
	v_ashrrev_i32_e32 v25, 31, v24
	v_mov_b32_e32 v20, 1.0
	s_and_b64 vcc, exec, s[30:31]
	v_lshl_add_u64 v[0:1], v[24:25], 2, s[24:25]
	v_mov_b32_e32 v22, 1.0
	s_cbranch_vccz .LBB0_271
	global_load_dword v22, v[0:1], off
	global_load_dword v100, v[0:1], off offset:64
	global_load_dword v101, v[0:1], off offset:128
	global_load_dword v102, v[0:1], off offset:192
.LBB0_271:
	s_movk_i32 s4, 0x204
	v_lshlrev_b32_e32 v21, 2, v21
	s_waitcnt vmcnt(0)
	v_pk_mul_f32 v[24:25], v[16:17], v[22:23] op_sel_hi:[1,0]
	v_mul_lo_u32 v16, v23, s4
	v_cndmask_b32_e64 v17, 0, 1, s[30:31]
	v_add_u32_e32 v16, v21, v16
	v_pk_mul_f32 v[18:19], v[18:19], v[22:23] op_sel_hi:[1,0]
	v_cmp_ne_u32_e64 s[4:5], 1, v17
	s_andn2_b64 vcc, exec, s[30:31]
	ds_write2_b32 v16, v24, v25 offset1:1
	ds_write2_b32 v16, v18, v19 offset0:2 offset1:3
	s_cbranch_vccnz .LBB0_273
	v_mov_b32_e32 v20, v100
.LBB0_273:
	s_waitcnt vmcnt(0)
	v_pk_mul_f32 v[12:13], v[12:13], v[20:21] op_sel_hi:[1,0]
	v_add_u32_e32 v17, 0x2040, v16
	ds_write2_b32 v17, v12, v13 offset1:1
	v_pk_mul_f32 v[12:13], v[14:15], v[20:21] op_sel_hi:[1,0]
	v_add_u32_e32 v14, 0x2048, v16
	ds_write2_b32 v14, v12, v13 offset1:1
	v_mov_b32_e32 v12, 1.0
	s_and_b64 vcc, exec, s[4:5]
	v_mov_b32_e32 v14, 1.0
	s_cbranch_vccnz .LBB0_275
	v_mov_b32_e32 v14, v101
.LBB0_275:
	s_waitcnt vmcnt(0)
	v_pk_mul_f32 v[8:9], v[8:9], v[14:15] op_sel_hi:[1,0]
	v_add_u32_e32 v13, 0x4080, v16
	ds_write2_b32 v13, v8, v9 offset1:1
	v_pk_mul_f32 v[8:9], v[10:11], v[14:15] op_sel_hi:[1,0]
	v_add_u32_e32 v10, 0x4088, v16
	s_and_b64 vcc, exec, s[4:5]
	ds_write2_b32 v10, v8, v9 offset1:1
	s_cbranch_vccnz .LBB0_277
	v_mov_b32_e32 v12, v102

; DI void convert_tile(const float* __restrict__ W, int K, int N, const float* __restrict__ g, bf16_t* __restrict__ Wt, int mode, int kt, int nt, bool f16) {
;     ...
;   float* tile = (float*)smem;
;   {
;     const int nl = (t & 31) * 4;
;     const int n = nt * 128 + nl;
;     const int nc = min(n, N - 4);
;     float4 v[4];
; #pragma unroll
;     for (int i = 0; i < 4; ++i) v[i] = *(const float4*)(W + (size_t)(kt * 64 + (t >> 5) + 16 * i) * N + nc);
; #pragma unroll
;     for (int i = 0; i < 4; ++i) {
;       const int kl = (t >> 5) + 16 * i;
;       const float gs = g ? g[kt * 64 + kl] : 1.f;
;       tile[kl * 129 + nl + 0] = v[i].x * gs;
;       tile[kl * 129 + nl + 1] = v[i].y * gs;
;       tile[kl * 129 + nl + 2] = v[i].z * gs;
;       tile[kl * 129 + nl + 3] = v[i].w * gs;
;     }
.LBB0_282:
	s_mul_hi_i32 s4, s29, 0x2aaaaaab
	s_lshr_b32 s5, s4, 31
	v_mov_b32_e32 v3, v224
	s_add_i32 s4, s4, s5
	s_mul_i32 s33, s4, 0x300
	v_lshlrev_b32_e32 v0, 2, v3
	v_and_b32_e32 v21, 0x7c, v0
	v_subrev_u32_e32 v0, s33, v21
	v_add_u32_e32 v0, s1, v0
	v_min_i32_e32 v0, 0x2fc, v0
	s_lshl_b32 s36, s4, 6
	v_ashrrev_i32_e32 v23, 5, v3
	v_ashrrev_i32_e32 v1, 31, v0
	v_add_u32_e32 v24, s36, v23
	v_lshl_add_u64 v[0:1], v[0:1], 2, s[14:15]
	s_movk_i32 s37, 0xc00
	v_mad_i64_i32 v[4:5], s[4:5], v24, s37, v[0:1]
	v_add_u32_e32 v6, 16, v24
	v_mad_i64_i32 v[6:7], s[4:5], v6, s37, v[0:1]
	global_load_dwordx4 v[16:19], v[4:5], off
	global_load_dwordx4 v[12:15], v[6:7], off
	v_add_u32_e32 v4, 32, v24
	v_mad_i64_i32 v[4:5], s[4:5], v4, s37, v[0:1]
	v_add_u32_e32 v6, 48, v24
	v_mad_i64_i32 v[0:1], s[4:5], v6, s37, v[0:1]
	global_load_dwordx4 v[8:11], v[4:5], off
	s_nop 0
	global_load_dwordx4 v[4:7], v[0:1], off
	v_ashrrev_i32_e32 v25, 31, v24
	v_mov_b32_e32 v20, 1.0
	s_and_b64 vcc, exec, s[30:31]
	v_lshl_add_u64 v[0:1], v[24:25], 2, s[20:21]
	v_mov_b32_e32 v22, 1.0
	s_cbranch_vccz .LBB0_284
	global_load_dword v22, v[0:1], off
	global_load_dword v100, v[0:1], off offset:64
	global_load_dword v101, v[0:1], off offset:128
	global_load_dword v102, v[0:1], off offset:192

; DI void convert_tile(const float* __restrict__ W, int K, int N, const float* __restrict__ g, bf16_t* __restrict__ Wt, int mode, int kt, int nt, bool f16) {
;     ...
;   float* tile = (float*)smem;
;   {
;     const int nl = (t & 31) * 4;
;     const int n = nt * 128 + nl;
;     const int nc = min(n, N - 4);
;     float4 v[4];
; #pragma unroll
;     for (int i = 0; i < 4; ++i) v[i] = *(const float4*)(W + (size_t)(kt * 64 + (t >> 5) + 16 * i) * N + nc);
; #pragma unroll
;     for (int i = 0; i < 4; ++i) {
;       const int kl = (t >> 5) + 16 * i;
;       const float gs = g ? g[kt * 64 + kl] : 1.f;
;       tile[kl * 129 + nl + 0] = v[i].x * gs;
;       tile[kl * 129 + nl + 1] = v[i].y * gs;
;       tile[kl * 129 + nl + 2] = v[i].z * gs;
;       tile[kl * 129 + nl + 3] = v[i].w * gs;
;     }
.LBB0_295:
	s_ashr_i32 s4, s29, 31
	s_lshr_b32 s4, s4, 29
	s_add_i32 s4, s29, s4
	v_mov_b32_e32 v3, v224
	s_ashr_i32 s4, s4, 3
	s_lshl_b32 s33, s4, 10
	v_lshlrev_b32_e32 v0, 2, v3
	v_and_b32_e32 v21, 0x7c, v0
	v_subrev_u32_e32 v0, s33, v21
	v_add_u32_e32 v0, s1, v0
	s_lshl_b32 s36, s4, 6
	v_ashrrev_i32_e32 v23, 5, v3
	v_min_i32_e32 v0, 0x3fc, v0
	v_add_u32_e32 v24, s36, v23
	v_ashrrev_i32_e32 v1, 31, v0
	v_ashrrev_i32_e32 v25, 31, v24
	v_lshl_add_u64 v[0:1], v[0:1], 2, s[14:15]
	v_lshlrev_b64 v[4:5], 12, v[24:25]
	v_lshl_add_u64 v[0:1], v[0:1], 0, v[4:5]
	s_mov_b32 s4, 0x10000
	v_add_co_u32_e32 v4, vcc, s4, v0
	v_mov_b32_e32 v20, 1.0
	s_nop 0
	v_addc_co_u32_e32 v5, vcc, 0, v1, vcc
	global_load_dwordx4 v[16:19], v[0:1], off
	global_load_dwordx4 v[12:15], v[4:5], off
	v_add_co_u32_e32 v4, vcc, 0x20000, v0
	v_mov_b32_e32 v22, 1.0
	s_nop 0
	v_addc_co_u32_e32 v5, vcc, 0, v1, vcc
	v_add_co_u32_e32 v0, vcc, 0x30000, v0
	s_nop 1
	v_addc_co_u32_e32 v1, vcc, 0, v1, vcc
	global_load_dwordx4 v[8:11], v[4:5], off
	s_nop 0
	global_load_dwordx4 v[4:7], v[0:1], off
	s_and_b64 vcc, exec, s[30:31]
	v_lshl_add_u64 v[0:1], v[24:25], 2, s[20:21]
	s_cbranch_vccz .LBB0_297
	global_load_dword v22, v[0:1], off
	global_load_dword v100, v[0:1], off offset:64
	global_load_dword v101, v[0:1], off offset:128
	global_load_dword v102, v[0:1], off offset:192

; DI void convert_tile(const float* __restrict__ W, int K, int N, const float* __restrict__ g, bf16_t* __restrict__ Wt, int mode, int kt, int nt, bool f16) {
;     ...
;   float* tile = (float*)smem;
;   {
;     const int nl = (t & 31) * 4;
;     const int n = nt * 128 + nl;
;     const int nc = min(n, N - 4);
;     float4 v[4];
; #pragma unroll
;     for (int i = 0; i < 4; ++i) v[i] = *(const float4*)(W + (size_t)(kt * 64 + (t >> 5) + 16 * i) * N + nc);
; #pragma unroll
;     for (int i = 0; i < 4; ++i) {
;       const int kl = (t >> 5) + 16 * i;
;       const float gs = g ? g[kt * 64 + kl] : 1.f;
;       tile[kl * 129 + nl + 0] = v[i].x * gs;
;       tile[kl * 129 + nl + 1] = v[i].y * gs;
;       tile[kl * 129 + nl + 2] = v[i].z * gs;
;       tile[kl * 129 + nl + 3] = v[i].w * gs;
;     }
.LBB0_316:
	s_ashr_i32 s4, s29, 31
	s_lshr_b32 s4, s4, 30
	s_add_i32 s4, s29, s4
	v_mov_b32_e32 v3, v224
	s_ashr_i32 s4, s4, 2
	s_lshl_b32 s33, s4, 9
	v_lshlrev_b32_e32 v0, 2, v3
	v_and_b32_e32 v21, 0x7c, v0
	v_subrev_u32_e32 v0, s33, v21
	v_add_u32_e32 v0, s7, v0
	s_lshl_b32 s40, s4, 6
	v_ashrrev_i32_e32 v23, 5, v3
	v_min_i32_e32 v0, 0x1fc, v0
	v_add_u32_e32 v24, s40, v23
	v_ashrrev_i32_e32 v1, 31, v0
	v_ashrrev_i32_e32 v25, 31, v24
	v_lshl_add_u64 v[0:1], v[0:1], 2, s[20:21]
	v_lshlrev_b64 v[4:5], 11, v[24:25]
	v_lshl_add_u64 v[0:1], v[0:1], 0, v[4:5]
	v_add_co_u32_e32 v4, vcc, 0x8000, v0
	v_mov_b32_e32 v20, 1.0
	s_nop 0
	v_addc_co_u32_e32 v5, vcc, 0, v1, vcc
	global_load_dwordx4 v[16:19], v[0:1], off
	global_load_dwordx4 v[12:15], v[4:5], off
	v_add_co_u32_e32 v4, vcc, 0x10000, v0
	v_mov_b32_e32 v22, 1.0
	s_nop 0
	v_addc_co_u32_e32 v5, vcc, 0, v1, vcc
	v_add_co_u32_e32 v0, vcc, 0x18000, v0
	s_nop 1
	v_addc_co_u32_e32 v1, vcc, 0, v1, vcc
	global_load_dwordx4 v[8:11], v[4:5], off
	s_nop 0
	global_load_dwordx4 v[4:7], v[0:1], off
	s_and_b64 vcc, exec, s[36:37]
	v_lshl_add_u64 v[0:1], v[24:25], 2, s[24:25]
	s_cbranch_vccz .LBB0_318
	global_load_dword v22, v[0:1], off
	global_load_dword v100, v[0:1], off offset:64
	global_load_dword v101, v[0:1], off offset:128
	global_load_dword v102, v[0:1], off offset:192
.LBB0_318:
	s_movk_i32 s4, 0x204
	v_lshlrev_b32_e32 v21, 2, v21
	s_waitcnt vmcnt(0)
	v_pk_mul_f32 v[24:25], v[16:17], v[22:23] op_sel_hi:[1,0]
	v_mul_lo_u32 v16, v23, s4
	v_cndmask_b32_e64 v17, 0, 1, s[36:37]
	v_add_u32_e32 v16, v21, v16
	v_pk_mul_f32 v[18:19], v[18:19], v[22:23] op_sel_hi:[1,0]
	v_cmp_ne_u32_e64 s[4:5], 1, v17
	s_andn2_b64 vcc, exec, s[36:37]
	ds_write2_b32 v16, v24, v25 offset1:1
	ds_write2_b32 v16, v18, v19 offset0:2 offset1:3
	s_cbranch_vccnz .LBB0_320
	v_mov_b32_e32 v20, v100

; DI void convert_tile(const float* __restrict__ W, int K, int N, const float* __restrict__ g, bf16_t* __restrict__ Wt, int mode, int kt, int nt, bool f16) {
;     ...
;   float* tile = (float*)smem;
;   {
;     const int nl = (t & 31) * 4;
;     const int n = nt * 128 + nl;
;     const int nc = min(n, N - 4);
;     float4 v[4];
; #pragma unroll
;     for (int i = 0; i < 4; ++i) v[i] = *(const float4*)(W + (size_t)(kt * 64 + (t >> 5) + 16 * i) * N + nc);
; #pragma unroll
;     for (int i = 0; i < 4; ++i) {
;       const int kl = (t >> 5) + 16 * i;
;       const float gs = g ? g[kt * 64 + kl] : 1.f;
;       tile[kl * 129 + nl + 0] = v[i].x * gs;
;       tile[kl * 129 + nl + 1] = v[i].y * gs;
;       tile[kl * 129 + nl + 2] = v[i].z * gs;
;       tile[kl * 129 + nl + 3] = v[i].w * gs;
;     }
.LBB0_329:
	s_ashr_i32 s4, s27, 31
	s_lshr_b32 s4, s4, 29
	s_add_i32 s4, s27, s4
	v_mov_b32_e32 v3, v224
	s_ashr_i32 s4, s4, 3
	s_lshl_b32 s29, s4, 10
	v_lshlrev_b32_e32 v0, 2, v3
	v_and_b32_e32 v21, 0x7c, v0
	v_subrev_u32_e32 v0, s29, v21
	v_add_u32_e32 v0, s1, v0
	s_lshl_b32 s40, s4, 6
	v_ashrrev_i32_e32 v23, 5, v3
	v_min_i32_e32 v0, 0x3fc, v0
	v_add_u32_e32 v24, s40, v23
	v_ashrrev_i32_e32 v1, 31, v0
	v_ashrrev_i32_e32 v25, 31, v24
	v_lshl_add_u64 v[0:1], v[0:1], 2, s[20:21]
	v_lshlrev_b64 v[4:5], 12, v[24:25]
	v_lshl_add_u64 v[0:1], v[0:1], 0, v[4:5]
	s_mov_b32 s4, 0x10000
	v_add_co_u32_e32 v4, vcc, s4, v0
	v_mov_b32_e32 v20, 1.0
	s_nop 0
	v_addc_co_u32_e32 v5, vcc, 0, v1, vcc
	global_load_dwordx4 v[16:19], v[0:1], off
	global_load_dwordx4 v[12:15], v[4:5], off
	v_add_co_u32_e32 v4, vcc, 0x20000, v0
	v_mov_b32_e32 v22, 1.0
	s_nop 0
	v_addc_co_u32_e32 v5, vcc, 0, v1, vcc
	v_add_co_u32_e32 v0, vcc, 0x30000, v0
	s_nop 1
	v_addc_co_u32_e32 v1, vcc, 0, v1, vcc
	global_load_dwordx4 v[8:11], v[4:5], off
	s_nop 0
	global_load_dwordx4 v[4:7], v[0:1], off
	s_and_b64 vcc, exec, s[36:37]
	v_lshl_add_u64 v[0:1], v[24:25], 2, s[24:25]
	s_cbranch_vccz .LBB0_331
	global_load_dword v22, v[0:1], off
	global_load_dword v100, v[0:1], off offset:64
	global_load_dword v101, v[0:1], off offset:128
	global_load_dword v102, v[0:1], off offset:192

; DI void convert_tile(const float* __restrict__ W, int K, int N, const float* __restrict__ g, bf16_t* __restrict__ Wt, int mode, int kt, int nt, bool f16) {
;     ...
;   float* tile = (float*)smem;
;   {
;     const int nl = (t & 31) * 4;
;     const int n = nt * 128 + nl;
;     const int nc = min(n, N - 4);
;     float4 v[4];
; #pragma unroll
;     for (int i = 0; i < 4; ++i) v[i] = *(const float4*)(W + (size_t)(kt * 64 + (t >> 5) + 16 * i) * N + nc);
; #pragma unroll
;     for (int i = 0; i < 4; ++i) {
;       const int kl = (t >> 5) + 16 * i;
;       const float gs = g ? g[kt * 64 + kl] : 1.f;
;       tile[kl * 129 + nl + 0] = v[i].x * gs;
;       tile[kl * 129 + nl + 1] = v[i].y * gs;
;       tile[kl * 129 + nl + 2] = v[i].z * gs;
;       tile[kl * 129 + nl + 3] = v[i].w * gs;
;     }
.LBB0_348:
	s_mul_hi_i32 s4, s27, 0x2e8ba2e9
	s_lshr_b32 s5, s4, 31
	s_ashr_i32 s4, s4, 3
	v_mov_b32_e32 v3, v224
	s_add_i32 s4, s4, s5
	s_mul_i32 s29, s4, 0x1600
	v_lshlrev_b32_e32 v0, 2, v3
	v_and_b32_e32 v21, 0x7c, v0
	v_subrev_u32_e32 v0, s29, v21
	v_add_u32_e32 v0, s1, v0
	v_min_i32_e32 v0, 0x15fc, v0
	s_lshl_b32 s30, s4, 6
	v_ashrrev_i32_e32 v23, 5, v3
	v_ashrrev_i32_e32 v1, 31, v0
	v_add_u32_e32 v24, s30, v23
	v_lshl_add_u64 v[0:1], v[0:1], 2, s[14:15]
	s_movk_i32 s31, 0x5800
	v_mad_i64_i32 v[4:5], s[4:5], v24, s31, v[0:1]
	v_add_u32_e32 v6, 16, v24
	v_mad_i64_i32 v[6:7], s[4:5], v6, s31, v[0:1]
	global_load_dwordx4 v[16:19], v[4:5], off
	global_load_dwordx4 v[12:15], v[6:7], off
	v_add_u32_e32 v4, 32, v24
	v_mad_i64_i32 v[4:5], s[4:5], v4, s31, v[0:1]
	v_add_u32_e32 v6, 48, v24
	v_mad_i64_i32 v[0:1], s[4:5], v6, s31, v[0:1]
	global_load_dwordx4 v[8:11], v[4:5], off
	s_nop 0
	global_load_dwordx4 v[4:7], v[0:1], off
	v_ashrrev_i32_e32 v25, 31, v24
	v_mov_b32_e32 v20, 1.0
	s_and_b64 vcc, exec, s[24:25]
	v_lshl_add_u64 v[0:1], v[24:25], 2, s[12:13]
	v_mov_b32_e32 v22, 1.0
	s_cbranch_vccz .LBB0_350
	global_load_dword v22, v[0:1], off
	global_load_dword v100, v[0:1], off offset:64
	global_load_dword v101, v[0:1], off offset:128
	global_load_dword v102, v[0:1], off offset:192
.LBB0_350:
	s_movk_i32 s4, 0x204
	v_lshlrev_b32_e32 v21, 2, v21
	s_waitcnt vmcnt(0)
	v_pk_mul_f32 v[24:25], v[16:17], v[22:23] op_sel_hi:[1,0]
	v_mul_lo_u32 v16, v23, s4
	v_cndmask_b32_e64 v17, 0, 1, s[24:25]
	v_add_u32_e32 v16, v21, v16
	v_pk_mul_f32 v[18:19], v[18:19], v[22:23] op_sel_hi:[1,0]
	v_cmp_ne_u32_e64 s[4:5], 1, v17
	s_andn2_b64 vcc, exec, s[24:25]
	ds_write2_b32 v16, v24, v25 offset1:1
	ds_write2_b32 v16, v18, v19 offset0:2 offset1:3
	s_cbranch_vccnz .LBB0_352
	v_mov_b32_e32 v20, v100

; DI void convert_tile(const float* __restrict__ W, int K, int N, const float* __restrict__ g, bf16_t* __restrict__ Wt, int mode, int kt, int nt, bool f16) {
;     ...
;   float* tile = (float*)smem;
;   {
;     const int nl = (t & 31) * 4;
;     const int n = nt * 128 + nl;
;     const int nc = min(n, N - 4);
;     float4 v[4];
; #pragma unroll
;     for (int i = 0; i < 4; ++i) v[i] = *(const float4*)(W + (size_t)(kt * 64 + (t >> 5) + 16 * i) * N + nc);
; #pragma unroll
;     for (int i = 0; i < 4; ++i) {
;       const int kl = (t >> 5) + 16 * i;
;       const float gs = g ? g[kt * 64 + kl] : 1.f;
;       tile[kl * 129 + nl + 0] = v[i].x * gs;
;       tile[kl * 129 + nl + 1] = v[i].y * gs;
;       tile[kl * 129 + nl + 2] = v[i].z * gs;
;       tile[kl * 129 + nl + 3] = v[i].w * gs;
;     }
.LBB0_372:
	s_ashr_i32 s4, s29, 31
	s_lshr_b32 s4, s4, 28
	s_add_i32 s4, s29, s4
	v_mov_b32_e32 v3, v224
	s_ashr_i32 s4, s4, 4
	s_lshl_b32 s25, s4, 11
	v_lshlrev_b32_e32 v0, 2, v3
	v_and_b32_e32 v21, 0x7c, v0
	v_subrev_u32_e32 v0, s25, v21
	v_add_u32_e32 v0, s7, v0
	v_min_i32_e32 v0, 0x79c, v0
	s_lshl_b32 s24, s4, 6
	v_ashrrev_i32_e32 v23, 5, v3
	v_ashrrev_i32_e32 v1, 31, v0
	v_add_u32_e32 v24, s24, v23
	v_lshl_add_u64 v[0:1], v[0:1], 2, s[12:13]
	s_movk_i32 s31, 0x1e80
	v_mad_i64_i32 v[4:5], s[4:5], v24, s31, v[0:1]
	v_add_u32_e32 v6, 16, v24
	v_mad_i64_i32 v[6:7], s[4:5], v6, s31, v[0:1]
	global_load_dwordx4 v[16:19], v[4:5], off
	global_load_dwordx4 v[12:15], v[6:7], off
	v_add_u32_e32 v4, 32, v24
	v_mad_i64_i32 v[4:5], s[4:5], v4, s31, v[0:1]
	v_add_u32_e32 v6, 48, v24
	v_mad_i64_i32 v[0:1], s[4:5], v6, s31, v[0:1]
	global_load_dwordx4 v[8:11], v[4:5], off
	s_nop 0
	global_load_dwordx4 v[4:7], v[0:1], off
	v_ashrrev_i32_e32 v25, 31, v24
	v_mov_b32_e32 v20, 1.0
	s_and_b64 vcc, exec, s[20:21]
	v_lshl_add_u64 v[0:1], v[24:25], 2, s[14:15]
	v_mov_b32_e32 v22, 1.0
	s_cbranch_vccz .LBB0_374
	global_load_dword v22, v[0:1], off
	global_load_dword v100, v[0:1], off offset:64
	global_load_dword v101, v[0:1], off offset:128
	global_load_dword v102, v[0:1], off offset:192
.LBB0_374:
	s_movk_i32 s4, 0x204
	v_lshlrev_b32_e32 v21, 2, v21
	s_waitcnt vmcnt(0)
	v_pk_mul_f32 v[24:25], v[16:17], v[22:23] op_sel_hi:[1,0]
	v_mul_lo_u32 v16, v23, s4
	v_cndmask_b32_e64 v17, 0, 1, s[20:21]
	v_add_u32_e32 v16, v21, v16
	v_pk_mul_f32 v[18:19], v[18:19], v[22:23] op_sel_hi:[1,0]
	v_cmp_ne_u32_e64 s[4:5], 1, v17
	s_andn2_b64 vcc, exec, s[20:21]
	ds_write2_b32 v16, v24, v25 offset1:1
	ds_write2_b32 v16, v18, v19 offset0:2 offset1:3
	s_cbranch_vccnz .LBB0_376
	v_mov_b32_e32 v20, v100

; DI void convert_tile(const float* __restrict__ W, int K, int N, const float* __restrict__ g, bf16_t* __restrict__ Wt, int mode, int kt, int nt, bool f16) {
;     ...
;   float* tile = (float*)smem;
;   {
;     const int nl = (t & 31) * 4;
;     const int n = nt * 128 + nl;
;     const int nc = min(n, N - 4);
;     float4 v[4];
; #pragma unroll
;     for (int i = 0; i < 4; ++i) v[i] = *(const float4*)(W + (size_t)(kt * 64 + (t >> 5) + 16 * i) * N + nc);
; #pragma unroll
;     for (int i = 0; i < 4; ++i) {
;       const int kl = (t >> 5) + 16 * i;
;       const float gs = g ? g[kt * 64 + kl] : 1.f;
;       tile[kl * 129 + nl + 0] = v[i].x * gs;
;       tile[kl * 129 + nl + 1] = v[i].y * gs;
;       tile[kl * 129 + nl + 2] = v[i].z * gs;
;       tile[kl * 129 + nl + 3] = v[i].w * gs;
;     }
.LBB0_385:
	s_mul_hi_i32 s4, s29, 0x2aaaaaab
	s_lshr_b32 s5, s4, 31
	v_mov_b32_e32 v3, v224
	s_add_i32 s4, s4, s5
	s_mul_i32 s31, s4, 0x300
	v_lshlrev_b32_e32 v0, 2, v3
	v_and_b32_e32 v21, 0x7c, v0
	v_subrev_u32_e32 v0, s31, v21
	v_add_u32_e32 v0, s7, v0
	v_min_i32_e32 v0, 0x2fc, v0
	s_lshl_b32 s36, s4, 6
	v_ashrrev_i32_e32 v23, 5, v3
	v_ashrrev_i32_e32 v1, 31, v0
	v_add_u32_e32 v24, s36, v23
	v_lshl_add_u64 v[0:1], v[0:1], 2, s[12:13]
	s_movk_i32 s33, 0xc00
	v_mad_i64_i32 v[4:5], s[4:5], v24, s33, v[0:1]
	v_add_u32_e32 v6, 16, v24
	v_mad_i64_i32 v[6:7], s[4:5], v6, s33, v[0:1]
	global_load_dwordx4 v[16:19], v[4:5], off
	global_load_dwordx4 v[12:15], v[6:7], off
	v_add_u32_e32 v4, 32, v24
	v_mad_i64_i32 v[4:5], s[4:5], v4, s33, v[0:1]
	v_add_u32_e32 v6, 48, v24
	v_mad_i64_i32 v[0:1], s[4:5], v6, s33, v[0:1]
	global_load_dwordx4 v[8:11], v[4:5], off
	s_nop 0
	global_load_dwordx4 v[4:7], v[0:1], off
	v_ashrrev_i32_e32 v25, 31, v24
	v_mov_b32_e32 v20, 1.0
	s_and_b64 vcc, exec, s[24:25]
	v_lshl_add_u64 v[0:1], v[24:25], 2, s[14:15]
	v_mov_b32_e32 v22, 1.0
	s_cbranch_vccz .LBB0_387
	global_load_dword v22, v[0:1], off
	global_load_dword v100, v[0:1], off offset:64
	global_load_dword v101, v[0:1], off offset:128
	global_load_dword v102, v[0:1], off offset:192

; DI void convert_tile(const float* __restrict__ W, int K, int N, const float* __restrict__ g, bf16_t* __restrict__ Wt, int mode, int kt, int nt, bool f16) {
;     ...
;   float* tile = (float*)smem;
;   {
;     const int nl = (t & 31) * 4;
;     const int n = nt * 128 + nl;
;     const int nc = min(n, N - 4);
;     float4 v[4];
; #pragma unroll
;     for (int i = 0; i < 4; ++i) v[i] = *(const float4*)(W + (size_t)(kt * 64 + (t >> 5) + 16 * i) * N + nc);
; #pragma unroll
;     for (int i = 0; i < 4; ++i) {
;       const int kl = (t >> 5) + 16 * i;
;       const float gs = g ? g[kt * 64 + kl] : 1.f;
;       tile[kl * 129 + nl + 0] = v[i].x * gs;
;       tile[kl * 129 + nl + 1] = v[i].y * gs;
;       tile[kl * 129 + nl + 2] = v[i].z * gs;
;       tile[kl * 129 + nl + 3] = v[i].w * gs;
;     }
.LBB0_398:
	s_ashr_i32 s4, s29, 31
	s_lshr_b32 s4, s4, 29
	s_add_i32 s4, s29, s4
	v_mov_b32_e32 v3, v224
	s_ashr_i32 s4, s4, 3
	s_lshl_b32 s31, s4, 10
	v_lshlrev_b32_e32 v0, 2, v3
	v_and_b32_e32 v21, 0x7c, v0
	v_subrev_u32_e32 v0, s31, v21
	v_add_u32_e32 v0, s7, v0
	s_lshl_b32 s36, s4, 6
	v_ashrrev_i32_e32 v23, 5, v3
	v_min_i32_e32 v0, 0x3fc, v0
	v_add_u32_e32 v24, s36, v23
	v_ashrrev_i32_e32 v1, 31, v0
	v_ashrrev_i32_e32 v25, 31, v24
	v_lshl_add_u64 v[0:1], v[0:1], 2, s[12:13]
	v_lshlrev_b64 v[4:5], 12, v[24:25]
	v_lshl_add_u64 v[0:1], v[0:1], 0, v[4:5]
	s_mov_b32 s4, 0x10000
	v_add_co_u32_e32 v4, vcc, s4, v0
	v_mov_b32_e32 v20, 1.0
	s_nop 0
	v_addc_co_u32_e32 v5, vcc, 0, v1, vcc
	global_load_dwordx4 v[16:19], v[0:1], off
	global_load_dwordx4 v[12:15], v[4:5], off
	v_add_co_u32_e32 v4, vcc, 0x20000, v0
	v_mov_b32_e32 v22, 1.0
	s_nop 0
	v_addc_co_u32_e32 v5, vcc, 0, v1, vcc
	v_add_co_u32_e32 v0, vcc, 0x30000, v0
	s_nop 1
	v_addc_co_u32_e32 v1, vcc, 0, v1, vcc
	global_load_dwordx4 v[8:11], v[4:5], off
	s_nop 0
	global_load_dwordx4 v[4:7], v[0:1], off
	s_and_b64 vcc, exec, s[24:25]
	v_lshl_add_u64 v[0:1], v[24:25], 2, s[14:15]
	s_cbranch_vccz .LBB0_400
	global_load_dword v22, v[0:1], off
	global_load_dword v100, v[0:1], off offset:64
	global_load_dword v101, v[0:1], off offset:128
	global_load_dword v102, v[0:1], off offset:192

; DI void convert_tile(const float* __restrict__ W, int K, int N, const float* __restrict__ g, bf16_t* __restrict__ Wt, int mode, int kt, int nt, bool f16) {
;     ...
;   float* tile = (float*)smem;
;   {
;     const int nl = (t & 31) * 4;
;     const int n = nt * 128 + nl;
;     const int nc = min(n, N - 4);
;     float4 v[4];
; #pragma unroll
;     for (int i = 0; i < 4; ++i) v[i] = *(const float4*)(W + (size_t)(kt * 64 + (t >> 5) + 16 * i) * N + nc);
; #pragma unroll
;     for (int i = 0; i < 4; ++i) {
;       const int kl = (t >> 5) + 16 * i;
;       const float gs = g ? g[kt * 64 + kl] : 1.f;
;       tile[kl * 129 + nl + 0] = v[i].x * gs;
;       tile[kl * 129 + nl + 1] = v[i].y * gs;
;       tile[kl * 129 + nl + 2] = v[i].z * gs;
;       tile[kl * 129 + nl + 3] = v[i].w * gs;
;     }
.LBB0_421:
	s_mul_hi_i32 s4, s25, 0x2aaaaaab
	s_lshr_b32 s5, s4, 31
	s_ashr_i32 s4, s4, 1
	v_mov_b32_e32 v3, v224
	s_add_i32 s4, s4, s5
	s_mul_i32 s21, s4, 0x600
	v_lshlrev_b32_e32 v0, 2, v3
	v_and_b32_e32 v21, 0x7c, v0
	v_subrev_u32_e32 v0, s21, v21
	v_add_u32_e32 v0, s7, v0
	v_min_i32_e32 v0, 0x5fc, v0
	s_lshl_b32 s20, s4, 6
	v_ashrrev_i32_e32 v23, 5, v3
	v_ashrrev_i32_e32 v1, 31, v0
	v_add_u32_e32 v24, s20, v23
	v_lshl_add_u64 v[0:1], v[0:1], 2, s[2:3]
	s_movk_i32 s27, 0x1800
	v_mad_i64_i32 v[4:5], s[4:5], v24, s27, v[0:1]
	v_add_u32_e32 v6, 16, v24
	v_mad_i64_i32 v[6:7], s[4:5], v6, s27, v[0:1]
	global_load_dwordx4 v[16:19], v[4:5], off
	global_load_dwordx4 v[12:15], v[6:7], off
	v_add_u32_e32 v4, 32, v24
	v_mad_i64_i32 v[4:5], s[4:5], v4, s27, v[0:1]
	v_add_u32_e32 v6, 48, v24
	v_mad_i64_i32 v[0:1], s[4:5], v6, s27, v[0:1]
	global_load_dwordx4 v[8:11], v[4:5], off
	s_nop 0
	global_load_dwordx4 v[4:7], v[0:1], off
	v_ashrrev_i32_e32 v25, 31, v24
	v_mov_b32_e32 v20, 1.0
	s_and_b64 vcc, exec, s[14:15]
	v_lshl_add_u64 v[0:1], v[24:25], 2, s[12:13]
	v_mov_b32_e32 v22, 1.0
	s_cbranch_vccz .LBB0_423
	global_load_dword v22, v[0:1], off
	global_load_dword v100, v[0:1], off offset:64
	global_load_dword v101, v[0:1], off offset:128
	global_load_dword v102, v[0:1], off offset:192
.LBB0_423:
	s_movk_i32 s4, 0x204
	v_lshlrev_b32_e32 v21, 2, v21
	s_waitcnt vmcnt(0)
	v_pk_mul_f32 v[24:25], v[16:17], v[22:23] op_sel_hi:[1,0]
	v_mul_lo_u32 v16, v23, s4
	v_cndmask_b32_e64 v17, 0, 1, s[14:15]
	v_add_u32_e32 v16, v21, v16
	v_pk_mul_f32 v[18:19], v[18:19], v[22:23] op_sel_hi:[1,0]
	v_cmp_ne_u32_e64 s[4:5], 1, v17
	s_andn2_b64 vcc, exec, s[14:15]
	ds_write2_b32 v16, v24, v25 offset1:1
	ds_write2_b32 v16, v18, v19 offset0:2 offset1:3
	s_cbranch_vccnz .LBB0_425
	v_mov_b32_e32 v20, v100

; DI void convert_tile(const float* __restrict__ W, int K, int N, const float* __restrict__ g, bf16_t* __restrict__ Wt, int mode, int kt, int nt, bool f16) {
;     ...
;   float* tile = (float*)smem;
;   {
;     const int nl = (t & 31) * 4;
;     const int n = nt * 128 + nl;
;     const int nc = min(n, N - 4);
;     float4 v[4];
; #pragma unroll
;     for (int i = 0; i < 4; ++i) v[i] = *(const float4*)(W + (size_t)(kt * 64 + (t >> 5) + 16 * i) * N + nc);
; #pragma unroll
;     for (int i = 0; i < 4; ++i) {
;       const int kl = (t >> 5) + 16 * i;
;       const float gs = g ? g[kt * 64 + kl] : 1.f;
;       tile[kl * 129 + nl + 0] = v[i].x * gs;
;       tile[kl * 129 + nl + 1] = v[i].y * gs;
;       tile[kl * 129 + nl + 2] = v[i].z * gs;
;       tile[kl * 129 + nl + 3] = v[i].w * gs;
;     }
.LBB0_440:
	s_ashr_i32 s4, s27, 31
	s_lshr_b32 s4, s4, 30
	s_add_i32 s4, s27, s4
	v_mov_b32_e32 v3, v224
	s_ashr_i32 s4, s4, 2
	s_lshl_b32 s25, s4, 9
	v_lshlrev_b32_e32 v0, 2, v3
	v_and_b32_e32 v21, 0x7c, v0
	v_subrev_u32_e32 v0, s25, v21
	v_add_u32_e32 v0, s29, v0
	s_lshl_b32 s24, s4, 6
	v_ashrrev_i32_e32 v23, 5, v3
	v_min_i32_e32 v0, 0x1fc, v0
	v_add_u32_e32 v24, s24, v23
	v_ashrrev_i32_e32 v1, 31, v0
	v_ashrrev_i32_e32 v25, 31, v24
	v_lshl_add_u64 v[0:1], v[0:1], 2, s[2:3]
	v_lshlrev_b64 v[4:5], 11, v[24:25]
	v_lshl_add_u64 v[0:1], v[0:1], 0, v[4:5]
	v_add_co_u32_e32 v4, vcc, 0x8000, v0
	v_mov_b32_e32 v20, 1.0
	s_nop 0
	v_addc_co_u32_e32 v5, vcc, 0, v1, vcc
	global_load_dwordx4 v[16:19], v[0:1], off
	global_load_dwordx4 v[12:15], v[4:5], off
	v_add_co_u32_e32 v4, vcc, 0x10000, v0
	v_mov_b32_e32 v22, 1.0
	s_nop 0
	v_addc_co_u32_e32 v5, vcc, 0, v1, vcc
	v_add_co_u32_e32 v0, vcc, 0x18000, v0
	s_nop 1
	v_addc_co_u32_e32 v1, vcc, 0, v1, vcc
	global_load_dwordx4 v[8:11], v[4:5], off
	s_nop 0
	global_load_dwordx4 v[4:7], v[0:1], off
	s_and_b64 vcc, exec, s[20:21]
	v_lshl_add_u64 v[0:1], v[24:25], 2, s[12:13]
	s_cbranch_vccz .LBB0_442
	global_load_dword v22, v[0:1], off
	global_load_dword v100, v[0:1], off offset:64
	global_load_dword v101, v[0:1], off offset:128
	global_load_dword v102, v[0:1], off offset:192

; DI void convert_tile(const float* __restrict__ W, int K, int N, const float* __restrict__ g, bf16_t* __restrict__ Wt, int mode, int kt, int nt, bool f16) {
;     ...
;   float* tile = (float*)smem;
;   {
;     const int nl = (t & 31) * 4;
;     const int n = nt * 128 + nl;
;     const int nc = min(n, N - 4);
;     float4 v[4];
; #pragma unroll
;     for (int i = 0; i < 4; ++i) v[i] = *(const float4*)(W + (size_t)(kt * 64 + (t >> 5) + 16 * i) * N + nc);
; #pragma unroll
;     for (int i = 0; i < 4; ++i) {
;       const int kl = (t >> 5) + 16 * i;
;       const float gs = g ? g[kt * 64 + kl] : 1.f;
;       tile[kl * 129 + nl + 0] = v[i].x * gs;
;       tile[kl * 129 + nl + 1] = v[i].y * gs;
;       tile[kl * 129 + nl + 2] = v[i].z * gs;
;       tile[kl * 129 + nl + 3] = v[i].w * gs;
;     }
.LBB0_453:
	s_ashr_i32 s4, s27, 31
	s_lshr_b32 s4, s4, 29
	s_add_i32 s4, s27, s4
	v_mov_b32_e32 v3, v224
	s_ashr_i32 s4, s4, 3
	s_lshl_b32 s25, s4, 10
	v_lshlrev_b32_e32 v0, 2, v3
	v_and_b32_e32 v21, 0x7c, v0
	v_subrev_u32_e32 v0, s25, v21
	v_add_u32_e32 v0, s29, v0
	s_lshl_b32 s24, s4, 6
	v_ashrrev_i32_e32 v23, 5, v3
	v_min_i32_e32 v0, 0x3fc, v0
	v_add_u32_e32 v24, s24, v23
	v_ashrrev_i32_e32 v1, 31, v0
	v_ashrrev_i32_e32 v25, 31, v24
	v_lshl_add_u64 v[0:1], v[0:1], 2, s[2:3]
	v_lshlrev_b64 v[4:5], 12, v[24:25]
	v_lshl_add_u64 v[0:1], v[0:1], 0, v[4:5]
	s_mov_b32 s4, 0x10000
	v_add_co_u32_e32 v4, vcc, s4, v0
	v_mov_b32_e32 v20, 1.0
	s_nop 0
	v_addc_co_u32_e32 v5, vcc, 0, v1, vcc
	global_load_dwordx4 v[16:19], v[0:1], off
	global_load_dwordx4 v[12:15], v[4:5], off
	v_add_co_u32_e32 v4, vcc, 0x20000, v0
	v_mov_b32_e32 v22, 1.0
	s_nop 0
	v_addc_co_u32_e32 v5, vcc, 0, v1, vcc
	v_add_co_u32_e32 v0, vcc, 0x30000, v0
	s_nop 1
	v_addc_co_u32_e32 v1, vcc, 0, v1, vcc
	global_load_dwordx4 v[8:11], v[4:5], off
	s_nop 0
	global_load_dwordx4 v[4:7], v[0:1], off
	s_and_b64 vcc, exec, s[20:21]
	v_lshl_add_u64 v[0:1], v[24:25], 2, s[12:13]
	s_cbranch_vccz .LBB0_455
	global_load_dword v22, v[0:1], off
	global_load_dword v100, v[0:1], off offset:64
	global_load_dword v101, v[0:1], off offset:128
	global_load_dword v102, v[0:1], off offset:192

; DI void convert_tile(const float* __restrict__ W, int K, int N, const float* __restrict__ g, bf16_t* __restrict__ Wt, int mode, int kt, int nt, bool f16) {
;     ...
;   float* tile = (float*)smem;
;   {
;     const int nl = (t & 31) * 4;
;     const int n = nt * 128 + nl;
;     const int nc = min(n, N - 4);
;     float4 v[4];
; #pragma unroll
;     for (int i = 0; i < 4; ++i) v[i] = *(const float4*)(W + (size_t)(kt * 64 + (t >> 5) + 16 * i) * N + nc);
; #pragma unroll
;     for (int i = 0; i < 4; ++i) {
;       const int kl = (t >> 5) + 16 * i;
;       const float gs = g ? g[kt * 64 + kl] : 1.f;
;       tile[kl * 129 + nl + 0] = v[i].x * gs;
;       tile[kl * 129 + nl + 1] = v[i].y * gs;
;       tile[kl * 129 + nl + 2] = v[i].z * gs;
;       tile[kl * 129 + nl + 3] = v[i].w * gs;
;     }
.LBB0_472:
	s_mul_hi_i32 s4, s27, 0x2e8ba2e9
	s_lshr_b32 s5, s4, 31
	s_ashr_i32 s4, s4, 3
	v_mov_b32_e32 v3, v224
	s_add_i32 s4, s4, s5
	s_mul_i32 s21, s4, 0x1600
	v_lshlrev_b32_e32 v0, 2, v3
	v_and_b32_e32 v21, 0x7c, v0
	v_subrev_u32_e32 v0, s21, v21
	v_add_u32_e32 v0, s29, v0
	v_min_i32_e32 v0, 0x15fc, v0
	s_lshl_b32 s20, s4, 6
	v_ashrrev_i32_e32 v23, 5, v3
	v_ashrrev_i32_e32 v1, 31, v0
	v_add_u32_e32 v24, s20, v23
	v_lshl_add_u64 v[0:1], v[0:1], 2, s[0:1]
	s_movk_i32 s24, 0x5800
	v_mad_i64_i32 v[4:5], s[4:5], v24, s24, v[0:1]
	v_add_u32_e32 v6, 16, v24
	v_mad_i64_i32 v[6:7], s[4:5], v6, s24, v[0:1]
	global_load_dwordx4 v[16:19], v[4:5], off
	global_load_dwordx4 v[12:15], v[6:7], off
	v_add_u32_e32 v4, 32, v24
	v_mad_i64_i32 v[4:5], s[4:5], v4, s24, v[0:1]
	v_add_u32_e32 v6, 48, v24
	v_mad_i64_i32 v[0:1], s[4:5], v6, s24, v[0:1]
	global_load_dwordx4 v[8:11], v[4:5], off
	s_nop 0
	global_load_dwordx4 v[4:7], v[0:1], off
	v_ashrrev_i32_e32 v25, 31, v24
	v_mov_b32_e32 v20, 1.0
	s_and_b64 vcc, exec, s[14:15]
	v_lshl_add_u64 v[0:1], v[24:25], 2, s[2:3]
	v_mov_b32_e32 v22, 1.0
	s_cbranch_vccz .LBB0_474
	global_load_dword v22, v[0:1], off
	global_load_dword v100, v[0:1], off offset:64
	global_load_dword v101, v[0:1], off offset:128
	global_load_dword v102, v[0:1], off offset:192
